# accumulator clear at every GEMM unit start with v_pk_mov_b32 (two registers per instruction)
# baseline (speedup 1.0000x reference)
.LBB0_237:
	s_ashr_i32 s45, s44, 31
	s_lshl_b64 s[60:61], s[44:45], 19
	s_add_u32 s62, s22, s60
	s_addc_u32 s63, s23, s61
	s_and_b64 s[60:61], s[46:47], exec
	s_cselect_b32 s9, s63, s7
	s_cselect_b32 s45, s62, s6
	s_ashr_i32 s43, s42, 31
	s_lshl_b64 s[60:61], s[42:43], 19
	s_add_u32 s64, s56, s60
	s_addc_u32 s65, s57, s61
	s_and_b64 s[60:61], s[46:47], exec
	s_cselect_b32 s43, s65, s67
	s_cselect_b32 s93, s64, s66
	s_add_u32 s6, s6, 0x40080
	s_addc_u32 s7, s7, 0
	s_add_u32 s94, s66, 0x100
	v_mov_b32_e32 v2, 0
	s_addc_u32 s95, s67, 0
	s_mov_b32 s96, -2
	v_mov_b32_e32 v3, v2
	v_pk_mov_b32 v[4:5], v[2:3], v[2:3] op_sel:[0,1]
	v_pk_mov_b32 v[6:7], v[2:3], v[2:3] op_sel:[0,1]
	v_pk_mov_b32 v[8:9], v[2:3], v[2:3] op_sel:[0,1]
	v_pk_mov_b32 v[10:11], v[2:3], v[2:3] op_sel:[0,1]
	v_pk_mov_b32 v[12:13], v[2:3], v[2:3] op_sel:[0,1]
	v_pk_mov_b32 v[14:15], v[2:3], v[2:3] op_sel:[0,1]
	v_pk_mov_b32 v[16:17], v[2:3], v[2:3] op_sel:[0,1]
	v_pk_mov_b32 v[18:19], v[2:3], v[2:3] op_sel:[0,1]
	v_pk_mov_b32 v[20:21], v[2:3], v[2:3] op_sel:[0,1]
	v_pk_mov_b32 v[22:23], v[2:3], v[2:3] op_sel:[0,1]
	v_pk_mov_b32 v[24:25], v[2:3], v[2:3] op_sel:[0,1]
	v_pk_mov_b32 v[26:27], v[2:3], v[2:3] op_sel:[0,1]
	v_pk_mov_b32 v[28:29], v[2:3], v[2:3] op_sel:[0,1]
	v_pk_mov_b32 v[30:31], v[2:3], v[2:3] op_sel:[0,1]
	v_pk_mov_b32 v[32:33], v[2:3], v[2:3] op_sel:[0,1]
	v_pk_mov_b32 v[34:35], v[2:3], v[2:3] op_sel:[0,1]
	v_pk_mov_b32 v[36:37], v[2:3], v[2:3] op_sel:[0,1]
	v_pk_mov_b32 v[38:39], v[2:3], v[2:3] op_sel:[0,1]
	v_pk_mov_b32 v[40:41], v[2:3], v[2:3] op_sel:[0,1]
	v_pk_mov_b32 v[42:43], v[2:3], v[2:3] op_sel:[0,1]
	v_pk_mov_b32 v[44:45], v[2:3], v[2:3] op_sel:[0,1]
	v_pk_mov_b32 v[46:47], v[2:3], v[2:3] op_sel:[0,1]
	v_pk_mov_b32 v[48:49], v[2:3], v[2:3] op_sel:[0,1]
	v_pk_mov_b32 v[50:51], v[2:3], v[2:3] op_sel:[0,1]
	v_pk_mov_b32 v[52:53], v[2:3], v[2:3] op_sel:[0,1]
	v_pk_mov_b32 v[54:55], v[2:3], v[2:3] op_sel:[0,1]
	v_pk_mov_b32 v[56:57], v[2:3], v[2:3] op_sel:[0,1]
	v_pk_mov_b32 v[58:59], v[2:3], v[2:3] op_sel:[0,1]
	v_pk_mov_b32 v[60:61], v[2:3], v[2:3] op_sel:[0,1]
	v_pk_mov_b32 v[62:63], v[2:3], v[2:3] op_sel:[0,1]
	v_pk_mov_b32 v[64:65], v[2:3], v[2:3] op_sel:[0,1]
	v_pk_mov_b32 v[66:67], v[2:3], v[2:3] op_sel:[0,1]
	v_pk_mov_b32 v[68:69], v[2:3], v[2:3] op_sel:[0,1]
	v_pk_mov_b32 v[70:71], v[2:3], v[2:3] op_sel:[0,1]
	v_pk_mov_b32 v[72:73], v[2:3], v[2:3] op_sel:[0,1]
	v_pk_mov_b32 v[74:75], v[2:3], v[2:3] op_sel:[0,1]
	v_pk_mov_b32 v[76:77], v[2:3], v[2:3] op_sel:[0,1]
	v_pk_mov_b32 v[78:79], v[2:3], v[2:3] op_sel:[0,1]
	v_pk_mov_b32 v[80:81], v[2:3], v[2:3] op_sel:[0,1]
	v_pk_mov_b32 v[82:83], v[2:3], v[2:3] op_sel:[0,1]
	v_pk_mov_b32 v[84:85], v[2:3], v[2:3] op_sel:[0,1]
	v_pk_mov_b32 v[86:87], v[2:3], v[2:3] op_sel:[0,1]
	v_pk_mov_b32 v[88:89], v[2:3], v[2:3] op_sel:[0,1]
	v_pk_mov_b32 v[90:91], v[2:3], v[2:3] op_sel:[0,1]
	v_pk_mov_b32 v[92:93], v[2:3], v[2:3] op_sel:[0,1]
	v_pk_mov_b32 v[94:95], v[2:3], v[2:3] op_sel:[0,1]
	v_pk_mov_b32 v[96:97], v[2:3], v[2:3] op_sel:[0,1]
	v_pk_mov_b32 v[98:99], v[2:3], v[2:3] op_sel:[0,1]
	v_pk_mov_b32 v[100:101], v[2:3], v[2:3] op_sel:[0,1]
	v_pk_mov_b32 v[102:103], v[2:3], v[2:3] op_sel:[0,1]
	v_pk_mov_b32 v[104:105], v[2:3], v[2:3] op_sel:[0,1]
	v_pk_mov_b32 v[106:107], v[2:3], v[2:3] op_sel:[0,1]
	v_pk_mov_b32 v[108:109], v[2:3], v[2:3] op_sel:[0,1]
	v_pk_mov_b32 v[110:111], v[2:3], v[2:3] op_sel:[0,1]
	v_pk_mov_b32 v[112:113], v[2:3], v[2:3] op_sel:[0,1]
	v_pk_mov_b32 v[114:115], v[2:3], v[2:3] op_sel:[0,1]
	v_pk_mov_b32 v[116:117], v[2:3], v[2:3] op_sel:[0,1]
	v_pk_mov_b32 v[118:119], v[2:3], v[2:3] op_sel:[0,1]
	v_pk_mov_b32 v[120:121], v[2:3], v[2:3] op_sel:[0,1]
	v_pk_mov_b32 v[122:123], v[2:3], v[2:3] op_sel:[0,1]
	v_pk_mov_b32 v[124:125], v[2:3], v[2:3] op_sel:[0,1]
	v_pk_mov_b32 v[126:127], v[2:3], v[2:3] op_sel:[0,1]
	v_pk_mov_b32 v[128:129], v[2:3], v[2:3] op_sel:[0,1]

.LBB0_492:
	s_ashr_i32 s25, s24, 31
	s_lshl_b64 s[28:29], s[24:25], 19
	s_add_u32 s28, s3, s28
	s_addc_u32 s29, s46, s29
	s_and_b64 s[30:31], s[4:5], exec
	s_cselect_b32 s25, s29, s41
	s_cselect_b32 s39, s28, s40
	s_ashr_i32 s19, s18, 31
	s_lshl_b64 s[30:31], s[18:19], 19
	s_add_u32 s30, s47, s30
	s_addc_u32 s31, s62, s31
	s_and_b64 s[44:45], s[4:5], exec
	s_cselect_b32 s19, s31, s43
	s_cselect_b32 s80, s30, s42
	s_add_u32 s40, s40, 0x40080
	s_addc_u32 s41, s41, 0
	s_add_u32 s81, s42, 0x100
	v_mov_b32_e32 v2, 0
	s_addc_u32 s82, s43, 0
	s_mov_b32 s83, -2
	s_waitcnt lgkmcnt(0)
	v_mov_b32_e32 v3, v2
	v_pk_mov_b32 v[4:5], v[2:3], v[2:3] op_sel:[0,1]
	v_pk_mov_b32 v[6:7], v[2:3], v[2:3] op_sel:[0,1]
	v_pk_mov_b32 v[8:9], v[2:3], v[2:3] op_sel:[0,1]
	v_pk_mov_b32 v[10:11], v[2:3], v[2:3] op_sel:[0,1]
	v_pk_mov_b32 v[12:13], v[2:3], v[2:3] op_sel:[0,1]
	v_pk_mov_b32 v[14:15], v[2:3], v[2:3] op_sel:[0,1]
	v_pk_mov_b32 v[16:17], v[2:3], v[2:3] op_sel:[0,1]
	v_pk_mov_b32 v[18:19], v[2:3], v[2:3] op_sel:[0,1]
	v_pk_mov_b32 v[20:21], v[2:3], v[2:3] op_sel:[0,1]
	v_pk_mov_b32 v[22:23], v[2:3], v[2:3] op_sel:[0,1]
	v_pk_mov_b32 v[24:25], v[2:3], v[2:3] op_sel:[0,1]
	v_pk_mov_b32 v[26:27], v[2:3], v[2:3] op_sel:[0,1]
	v_pk_mov_b32 v[28:29], v[2:3], v[2:3] op_sel:[0,1]
	v_pk_mov_b32 v[30:31], v[2:3], v[2:3] op_sel:[0,1]
	v_pk_mov_b32 v[32:33], v[2:3], v[2:3] op_sel:[0,1]
	v_pk_mov_b32 v[34:35], v[2:3], v[2:3] op_sel:[0,1]
	v_pk_mov_b32 v[36:37], v[2:3], v[2:3] op_sel:[0,1]
	v_pk_mov_b32 v[38:39], v[2:3], v[2:3] op_sel:[0,1]
	v_pk_mov_b32 v[40:41], v[2:3], v[2:3] op_sel:[0,1]
	v_pk_mov_b32 v[42:43], v[2:3], v[2:3] op_sel:[0,1]
	v_pk_mov_b32 v[44:45], v[2:3], v[2:3] op_sel:[0,1]
	v_pk_mov_b32 v[46:47], v[2:3], v[2:3] op_sel:[0,1]
	v_pk_mov_b32 v[48:49], v[2:3], v[2:3] op_sel:[0,1]
	v_pk_mov_b32 v[50:51], v[2:3], v[2:3] op_sel:[0,1]
	v_pk_mov_b32 v[52:53], v[2:3], v[2:3] op_sel:[0,1]
	v_pk_mov_b32 v[54:55], v[2:3], v[2:3] op_sel:[0,1]
	v_pk_mov_b32 v[56:57], v[2:3], v[2:3] op_sel:[0,1]
	v_pk_mov_b32 v[58:59], v[2:3], v[2:3] op_sel:[0,1]
	v_pk_mov_b32 v[60:61], v[2:3], v[2:3] op_sel:[0,1]
	v_pk_mov_b32 v[62:63], v[2:3], v[2:3] op_sel:[0,1]
	v_pk_mov_b32 v[64:65], v[2:3], v[2:3] op_sel:[0,1]
	v_pk_mov_b32 v[66:67], v[2:3], v[2:3] op_sel:[0,1]
	v_pk_mov_b32 v[68:69], v[2:3], v[2:3] op_sel:[0,1]
	v_pk_mov_b32 v[70:71], v[2:3], v[2:3] op_sel:[0,1]
	v_pk_mov_b32 v[72:73], v[2:3], v[2:3] op_sel:[0,1]
	v_pk_mov_b32 v[82:83], v[2:3], v[2:3] op_sel:[0,1]
	v_pk_mov_b32 v[84:85], v[2:3], v[2:3] op_sel:[0,1]
	v_pk_mov_b32 v[86:87], v[2:3], v[2:3] op_sel:[0,1]
	v_pk_mov_b32 v[88:89], v[2:3], v[2:3] op_sel:[0,1]
	v_pk_mov_b32 v[90:91], v[2:3], v[2:3] op_sel:[0,1]
	v_pk_mov_b32 v[92:93], v[2:3], v[2:3] op_sel:[0,1]
	v_pk_mov_b32 v[94:95], v[2:3], v[2:3] op_sel:[0,1]
	v_pk_mov_b32 v[96:97], v[2:3], v[2:3] op_sel:[0,1]
	v_pk_mov_b32 v[98:99], v[2:3], v[2:3] op_sel:[0,1]
	v_pk_mov_b32 v[100:101], v[2:3], v[2:3] op_sel:[0,1]
	v_pk_mov_b32 v[102:103], v[2:3], v[2:3] op_sel:[0,1]
	v_pk_mov_b32 v[104:105], v[2:3], v[2:3] op_sel:[0,1]
	v_pk_mov_b32 v[106:107], v[2:3], v[2:3] op_sel:[0,1]
	v_pk_mov_b32 v[108:109], v[2:3], v[2:3] op_sel:[0,1]
	v_pk_mov_b32 v[110:111], v[2:3], v[2:3] op_sel:[0,1]
	v_pk_mov_b32 v[112:113], v[2:3], v[2:3] op_sel:[0,1]
	v_pk_mov_b32 v[114:115], v[2:3], v[2:3] op_sel:[0,1]
	v_pk_mov_b32 v[116:117], v[2:3], v[2:3] op_sel:[0,1]
	v_pk_mov_b32 v[118:119], v[2:3], v[2:3] op_sel:[0,1]
	v_pk_mov_b32 v[120:121], v[2:3], v[2:3] op_sel:[0,1]
	v_pk_mov_b32 v[122:123], v[2:3], v[2:3] op_sel:[0,1]
	v_pk_mov_b32 v[124:125], v[2:3], v[2:3] op_sel:[0,1]
	v_pk_mov_b32 v[126:127], v[2:3], v[2:3] op_sel:[0,1]
	v_pk_mov_b32 v[128:129], v[2:3], v[2:3] op_sel:[0,1]
	v_pk_mov_b32 v[130:131], v[2:3], v[2:3] op_sel:[0,1]
	v_pk_mov_b32 v[132:133], v[2:3], v[2:3] op_sel:[0,1]
	v_pk_mov_b32 v[134:135], v[2:3], v[2:3] op_sel:[0,1]
	v_pk_mov_b32 v[136:137], v[2:3], v[2:3] op_sel:[0,1]

.LBB0_583:
	s_ashr_i32 s17, s16, 31
	s_lshl_b64 s[18:19], s[16:17], 19
	s_add_u32 s18, s22, s18
	s_addc_u32 s19, s23, s19
	s_and_b64 s[24:25], s[0:1], exec
	s_cselect_b32 s17, s19, s31
	s_cselect_b32 s71, s18, s30
	s_ashr_i32 s15, s14, 31
	s_lshl_b64 s[24:25], s[14:15], 19
	s_add_u32 s24, s42, s24
	s_addc_u32 s25, s43, s25
	s_and_b64 s[38:39], s[0:1], exec
	s_cselect_b32 s15, s25, s37
	s_cselect_b32 s72, s24, s36
	s_add_u32 s30, s30, 0x40080
	s_addc_u32 s31, s31, 0
	s_add_u32 s73, s36, 0x100
	v_mov_b32_e32 v2, 0
	s_addc_u32 s74, s37, 0
	s_mov_b32 s75, -2
	v_mov_b32_e32 v3, v2
	v_pk_mov_b32 v[4:5], v[2:3], v[2:3] op_sel:[0,1]
	v_pk_mov_b32 v[6:7], v[2:3], v[2:3] op_sel:[0,1]
	v_pk_mov_b32 v[8:9], v[2:3], v[2:3] op_sel:[0,1]
	v_pk_mov_b32 v[10:11], v[2:3], v[2:3] op_sel:[0,1]
	v_pk_mov_b32 v[12:13], v[2:3], v[2:3] op_sel:[0,1]
	v_pk_mov_b32 v[14:15], v[2:3], v[2:3] op_sel:[0,1]
	v_pk_mov_b32 v[16:17], v[2:3], v[2:3] op_sel:[0,1]
	v_pk_mov_b32 v[18:19], v[2:3], v[2:3] op_sel:[0,1]
	v_pk_mov_b32 v[20:21], v[2:3], v[2:3] op_sel:[0,1]
	v_pk_mov_b32 v[22:23], v[2:3], v[2:3] op_sel:[0,1]
	v_pk_mov_b32 v[24:25], v[2:3], v[2:3] op_sel:[0,1]
	v_pk_mov_b32 v[26:27], v[2:3], v[2:3] op_sel:[0,1]
	v_pk_mov_b32 v[28:29], v[2:3], v[2:3] op_sel:[0,1]
	v_pk_mov_b32 v[30:31], v[2:3], v[2:3] op_sel:[0,1]
	v_pk_mov_b32 v[32:33], v[2:3], v[2:3] op_sel:[0,1]
	v_pk_mov_b32 v[34:35], v[2:3], v[2:3] op_sel:[0,1]
	v_pk_mov_b32 v[36:37], v[2:3], v[2:3] op_sel:[0,1]
	v_pk_mov_b32 v[38:39], v[2:3], v[2:3] op_sel:[0,1]
	v_pk_mov_b32 v[40:41], v[2:3], v[2:3] op_sel:[0,1]
	v_pk_mov_b32 v[42:43], v[2:3], v[2:3] op_sel:[0,1]
	v_pk_mov_b32 v[44:45], v[2:3], v[2:3] op_sel:[0,1]
	v_pk_mov_b32 v[46:47], v[2:3], v[2:3] op_sel:[0,1]
	v_pk_mov_b32 v[48:49], v[2:3], v[2:3] op_sel:[0,1]
	v_pk_mov_b32 v[50:51], v[2:3], v[2:3] op_sel:[0,1]
	v_pk_mov_b32 v[52:53], v[2:3], v[2:3] op_sel:[0,1]
	v_pk_mov_b32 v[54:55], v[2:3], v[2:3] op_sel:[0,1]
	v_pk_mov_b32 v[56:57], v[2:3], v[2:3] op_sel:[0,1]
	v_pk_mov_b32 v[58:59], v[2:3], v[2:3] op_sel:[0,1]
	v_pk_mov_b32 v[60:61], v[2:3], v[2:3] op_sel:[0,1]
	v_pk_mov_b32 v[62:63], v[2:3], v[2:3] op_sel:[0,1]
	v_pk_mov_b32 v[64:65], v[2:3], v[2:3] op_sel:[0,1]
	v_pk_mov_b32 v[66:67], v[2:3], v[2:3] op_sel:[0,1]
	v_pk_mov_b32 v[68:69], v[2:3], v[2:3] op_sel:[0,1]
	v_pk_mov_b32 v[70:71], v[2:3], v[2:3] op_sel:[0,1]
	v_pk_mov_b32 v[72:73], v[2:3], v[2:3] op_sel:[0,1]
	v_pk_mov_b32 v[74:75], v[2:3], v[2:3] op_sel:[0,1]
	v_pk_mov_b32 v[76:77], v[2:3], v[2:3] op_sel:[0,1]
	v_pk_mov_b32 v[78:79], v[2:3], v[2:3] op_sel:[0,1]
	v_pk_mov_b32 v[80:81], v[2:3], v[2:3] op_sel:[0,1]
	v_pk_mov_b32 v[82:83], v[2:3], v[2:3] op_sel:[0,1]
	v_pk_mov_b32 v[84:85], v[2:3], v[2:3] op_sel:[0,1]
	v_pk_mov_b32 v[86:87], v[2:3], v[2:3] op_sel:[0,1]
	v_pk_mov_b32 v[88:89], v[2:3], v[2:3] op_sel:[0,1]
	v_pk_mov_b32 v[90:91], v[2:3], v[2:3] op_sel:[0,1]
	v_pk_mov_b32 v[92:93], v[2:3], v[2:3] op_sel:[0,1]
	v_pk_mov_b32 v[94:95], v[2:3], v[2:3] op_sel:[0,1]
	v_pk_mov_b32 v[96:97], v[2:3], v[2:3] op_sel:[0,1]
	v_pk_mov_b32 v[98:99], v[2:3], v[2:3] op_sel:[0,1]
	v_pk_mov_b32 v[100:101], v[2:3], v[2:3] op_sel:[0,1]
	v_pk_mov_b32 v[102:103], v[2:3], v[2:3] op_sel:[0,1]
	v_pk_mov_b32 v[104:105], v[2:3], v[2:3] op_sel:[0,1]
	v_pk_mov_b32 v[106:107], v[2:3], v[2:3] op_sel:[0,1]
	v_pk_mov_b32 v[108:109], v[2:3], v[2:3] op_sel:[0,1]
	v_pk_mov_b32 v[110:111], v[2:3], v[2:3] op_sel:[0,1]
	v_pk_mov_b32 v[112:113], v[2:3], v[2:3] op_sel:[0,1]
	v_pk_mov_b32 v[114:115], v[2:3], v[2:3] op_sel:[0,1]
	v_pk_mov_b32 v[116:117], v[2:3], v[2:3] op_sel:[0,1]
	v_pk_mov_b32 v[118:119], v[2:3], v[2:3] op_sel:[0,1]
	v_pk_mov_b32 v[120:121], v[2:3], v[2:3] op_sel:[0,1]
	v_pk_mov_b32 v[122:123], v[2:3], v[2:3] op_sel:[0,1]
	v_pk_mov_b32 v[124:125], v[2:3], v[2:3] op_sel:[0,1]
	v_pk_mov_b32 v[126:127], v[2:3], v[2:3] op_sel:[0,1]
	v_pk_mov_b32 v[128:129], v[2:3], v[2:3] op_sel:[0,1]

.LBB0_664:
	s_add_u32 s28, s28, 0xb0080
	s_addc_u32 s29, s29, 0
	s_add_u32 s73, s30, 0x100
	v_mov_b32_e32 v2, 0
	s_addc_u32 s74, s31, 0
	s_mov_b32 s75, -2
	s_waitcnt lgkmcnt(0)
	v_mov_b32_e32 v3, v2
	v_pk_mov_b32 v[4:5], v[2:3], v[2:3] op_sel:[0,1]
	v_pk_mov_b32 v[6:7], v[2:3], v[2:3] op_sel:[0,1]
	v_pk_mov_b32 v[8:9], v[2:3], v[2:3] op_sel:[0,1]
	v_pk_mov_b32 v[10:11], v[2:3], v[2:3] op_sel:[0,1]
	v_pk_mov_b32 v[12:13], v[2:3], v[2:3] op_sel:[0,1]
	v_pk_mov_b32 v[14:15], v[2:3], v[2:3] op_sel:[0,1]
	v_pk_mov_b32 v[16:17], v[2:3], v[2:3] op_sel:[0,1]
	v_pk_mov_b32 v[18:19], v[2:3], v[2:3] op_sel:[0,1]
	v_pk_mov_b32 v[20:21], v[2:3], v[2:3] op_sel:[0,1]
	v_pk_mov_b32 v[22:23], v[2:3], v[2:3] op_sel:[0,1]
	v_pk_mov_b32 v[24:25], v[2:3], v[2:3] op_sel:[0,1]
	v_pk_mov_b32 v[26:27], v[2:3], v[2:3] op_sel:[0,1]
	v_pk_mov_b32 v[28:29], v[2:3], v[2:3] op_sel:[0,1]
	v_pk_mov_b32 v[30:31], v[2:3], v[2:3] op_sel:[0,1]
	v_pk_mov_b32 v[32:33], v[2:3], v[2:3] op_sel:[0,1]
	v_pk_mov_b32 v[34:35], v[2:3], v[2:3] op_sel:[0,1]
	v_pk_mov_b32 v[36:37], v[2:3], v[2:3] op_sel:[0,1]
	v_pk_mov_b32 v[38:39], v[2:3], v[2:3] op_sel:[0,1]
	v_pk_mov_b32 v[40:41], v[2:3], v[2:3] op_sel:[0,1]
	v_pk_mov_b32 v[42:43], v[2:3], v[2:3] op_sel:[0,1]
	v_pk_mov_b32 v[44:45], v[2:3], v[2:3] op_sel:[0,1]
	v_pk_mov_b32 v[46:47], v[2:3], v[2:3] op_sel:[0,1]
	v_pk_mov_b32 v[48:49], v[2:3], v[2:3] op_sel:[0,1]
	v_pk_mov_b32 v[50:51], v[2:3], v[2:3] op_sel:[0,1]
	v_pk_mov_b32 v[52:53], v[2:3], v[2:3] op_sel:[0,1]
	v_pk_mov_b32 v[54:55], v[2:3], v[2:3] op_sel:[0,1]
	v_pk_mov_b32 v[56:57], v[2:3], v[2:3] op_sel:[0,1]
	v_pk_mov_b32 v[58:59], v[2:3], v[2:3] op_sel:[0,1]
	v_pk_mov_b32 v[60:61], v[2:3], v[2:3] op_sel:[0,1]
	v_pk_mov_b32 v[62:63], v[2:3], v[2:3] op_sel:[0,1]
	v_pk_mov_b32 v[64:65], v[2:3], v[2:3] op_sel:[0,1]
	v_pk_mov_b32 v[66:67], v[2:3], v[2:3] op_sel:[0,1]
	v_pk_mov_b32 v[68:69], v[2:3], v[2:3] op_sel:[0,1]
	v_pk_mov_b32 v[70:71], v[2:3], v[2:3] op_sel:[0,1]
	v_pk_mov_b32 v[72:73], v[2:3], v[2:3] op_sel:[0,1]
	v_pk_mov_b32 v[74:75], v[2:3], v[2:3] op_sel:[0,1]
	v_pk_mov_b32 v[76:77], v[2:3], v[2:3] op_sel:[0,1]
	v_pk_mov_b32 v[78:79], v[2:3], v[2:3] op_sel:[0,1]
	v_pk_mov_b32 v[80:81], v[2:3], v[2:3] op_sel:[0,1]
	v_pk_mov_b32 v[98:99], v[2:3], v[2:3] op_sel:[0,1]
	v_pk_mov_b32 v[100:101], v[2:3], v[2:3] op_sel:[0,1]
	v_pk_mov_b32 v[102:103], v[2:3], v[2:3] op_sel:[0,1]
	v_pk_mov_b32 v[104:105], v[2:3], v[2:3] op_sel:[0,1]
	v_pk_mov_b32 v[106:107], v[2:3], v[2:3] op_sel:[0,1]
	v_pk_mov_b32 v[108:109], v[2:3], v[2:3] op_sel:[0,1]
	v_pk_mov_b32 v[110:111], v[2:3], v[2:3] op_sel:[0,1]
	v_pk_mov_b32 v[112:113], v[2:3], v[2:3] op_sel:[0,1]
	v_pk_mov_b32 v[114:115], v[2:3], v[2:3] op_sel:[0,1]
	v_pk_mov_b32 v[116:117], v[2:3], v[2:3] op_sel:[0,1]
	v_pk_mov_b32 v[118:119], v[2:3], v[2:3] op_sel:[0,1]
	v_pk_mov_b32 v[120:121], v[2:3], v[2:3] op_sel:[0,1]
	v_pk_mov_b32 v[122:123], v[2:3], v[2:3] op_sel:[0,1]
	v_pk_mov_b32 v[124:125], v[2:3], v[2:3] op_sel:[0,1]
	v_pk_mov_b32 v[126:127], v[2:3], v[2:3] op_sel:[0,1]
	v_pk_mov_b32 v[128:129], v[2:3], v[2:3] op_sel:[0,1]
	v_pk_mov_b32 v[130:131], v[2:3], v[2:3] op_sel:[0,1]
	v_pk_mov_b32 v[132:133], v[2:3], v[2:3] op_sel:[0,1]
	v_pk_mov_b32 v[134:135], v[2:3], v[2:3] op_sel:[0,1]
	v_pk_mov_b32 v[136:137], v[2:3], v[2:3] op_sel:[0,1]
	v_pk_mov_b32 v[138:139], v[2:3], v[2:3] op_sel:[0,1]
	v_pk_mov_b32 v[140:141], v[2:3], v[2:3] op_sel:[0,1]
	v_pk_mov_b32 v[142:143], v[2:3], v[2:3] op_sel:[0,1]
	v_pk_mov_b32 v[144:145], v[2:3], v[2:3] op_sel:[0,1]

.LBB0_910:
	s_ashr_i32 s37, s36, 31
	s_ashr_i32 s31, s30, 31
	s_lshl_b64 s[38:39], s[30:31], 10
	s_lshl_b64 s[42:43], s[36:37], 20
	s_add_u32 s31, s48, s42
	s_addc_u32 s37, s49, s43
	s_add_u32 s38, s31, s38
	s_addc_u32 s39, s37, s39
	s_and_b64 s[42:43], s[0:1], exec
	s_cselect_b32 s31, s39, s41
	s_cselect_b32 s37, s38, s40
	s_add_u32 s77, s40, 0x100
	v_mov_b32_e32 v2, 0
	s_addc_u32 s78, s41, 0
	v_lshl_add_u64 v[146:147], s[40:41], 0, v[138:139]
	v_lshl_add_u64 v[148:149], s[40:41], 0, v[140:141]
	s_mov_b32 s79, -2
	s_mov_b64 s[40:41], 0
	v_mov_b32_e32 v3, v2
	v_pk_mov_b32 v[4:5], v[2:3], v[2:3] op_sel:[0,1]
	v_pk_mov_b32 v[6:7], v[2:3], v[2:3] op_sel:[0,1]
	v_pk_mov_b32 v[8:9], v[2:3], v[2:3] op_sel:[0,1]
	v_pk_mov_b32 v[10:11], v[2:3], v[2:3] op_sel:[0,1]
	v_pk_mov_b32 v[12:13], v[2:3], v[2:3] op_sel:[0,1]
	v_pk_mov_b32 v[14:15], v[2:3], v[2:3] op_sel:[0,1]
	v_pk_mov_b32 v[16:17], v[2:3], v[2:3] op_sel:[0,1]
	v_pk_mov_b32 v[18:19], v[2:3], v[2:3] op_sel:[0,1]
	v_pk_mov_b32 v[20:21], v[2:3], v[2:3] op_sel:[0,1]
	v_pk_mov_b32 v[22:23], v[2:3], v[2:3] op_sel:[0,1]
	v_pk_mov_b32 v[24:25], v[2:3], v[2:3] op_sel:[0,1]
	v_pk_mov_b32 v[26:27], v[2:3], v[2:3] op_sel:[0,1]
	v_pk_mov_b32 v[28:29], v[2:3], v[2:3] op_sel:[0,1]
	v_pk_mov_b32 v[30:31], v[2:3], v[2:3] op_sel:[0,1]
	v_pk_mov_b32 v[32:33], v[2:3], v[2:3] op_sel:[0,1]
	v_pk_mov_b32 v[34:35], v[2:3], v[2:3] op_sel:[0,1]
	v_pk_mov_b32 v[36:37], v[2:3], v[2:3] op_sel:[0,1]
	v_pk_mov_b32 v[38:39], v[2:3], v[2:3] op_sel:[0,1]
	v_pk_mov_b32 v[40:41], v[2:3], v[2:3] op_sel:[0,1]
	v_pk_mov_b32 v[42:43], v[2:3], v[2:3] op_sel:[0,1]
	v_pk_mov_b32 v[44:45], v[2:3], v[2:3] op_sel:[0,1]
	v_pk_mov_b32 v[46:47], v[2:3], v[2:3] op_sel:[0,1]
	v_pk_mov_b32 v[48:49], v[2:3], v[2:3] op_sel:[0,1]
	v_pk_mov_b32 v[50:51], v[2:3], v[2:3] op_sel:[0,1]
	v_pk_mov_b32 v[52:53], v[2:3], v[2:3] op_sel:[0,1]
	v_pk_mov_b32 v[54:55], v[2:3], v[2:3] op_sel:[0,1]
	v_pk_mov_b32 v[56:57], v[2:3], v[2:3] op_sel:[0,1]
	v_pk_mov_b32 v[58:59], v[2:3], v[2:3] op_sel:[0,1]
	v_pk_mov_b32 v[60:61], v[2:3], v[2:3] op_sel:[0,1]
	v_pk_mov_b32 v[62:63], v[2:3], v[2:3] op_sel:[0,1]
	v_pk_mov_b32 v[64:65], v[2:3], v[2:3] op_sel:[0,1]
	v_pk_mov_b32 v[66:67], v[2:3], v[2:3] op_sel:[0,1]
	v_pk_mov_b32 v[68:69], v[2:3], v[2:3] op_sel:[0,1]
	v_pk_mov_b32 v[70:71], v[2:3], v[2:3] op_sel:[0,1]
	v_pk_mov_b32 v[72:73], v[2:3], v[2:3] op_sel:[0,1]
	v_pk_mov_b32 v[74:75], v[2:3], v[2:3] op_sel:[0,1]
	v_pk_mov_b32 v[76:77], v[2:3], v[2:3] op_sel:[0,1]
	v_pk_mov_b32 v[78:79], v[2:3], v[2:3] op_sel:[0,1]
	v_pk_mov_b32 v[80:81], v[2:3], v[2:3] op_sel:[0,1]
	v_pk_mov_b32 v[82:83], v[2:3], v[2:3] op_sel:[0,1]
	v_pk_mov_b32 v[84:85], v[2:3], v[2:3] op_sel:[0,1]
	v_pk_mov_b32 v[86:87], v[2:3], v[2:3] op_sel:[0,1]
	v_pk_mov_b32 v[88:89], v[2:3], v[2:3] op_sel:[0,1]
	v_pk_mov_b32 v[90:91], v[2:3], v[2:3] op_sel:[0,1]
	v_pk_mov_b32 v[92:93], v[2:3], v[2:3] op_sel:[0,1]
	v_pk_mov_b32 v[94:95], v[2:3], v[2:3] op_sel:[0,1]
	v_pk_mov_b32 v[96:97], v[2:3], v[2:3] op_sel:[0,1]
	v_pk_mov_b32 v[98:99], v[2:3], v[2:3] op_sel:[0,1]
	v_pk_mov_b32 v[100:101], v[2:3], v[2:3] op_sel:[0,1]
	v_pk_mov_b32 v[102:103], v[2:3], v[2:3] op_sel:[0,1]
	v_pk_mov_b32 v[104:105], v[2:3], v[2:3] op_sel:[0,1]
	v_pk_mov_b32 v[106:107], v[2:3], v[2:3] op_sel:[0,1]
	v_pk_mov_b32 v[108:109], v[2:3], v[2:3] op_sel:[0,1]
	v_pk_mov_b32 v[110:111], v[2:3], v[2:3] op_sel:[0,1]
	v_pk_mov_b32 v[112:113], v[2:3], v[2:3] op_sel:[0,1]
	v_pk_mov_b32 v[114:115], v[2:3], v[2:3] op_sel:[0,1]
	v_pk_mov_b32 v[116:117], v[2:3], v[2:3] op_sel:[0,1]
	v_pk_mov_b32 v[118:119], v[2:3], v[2:3] op_sel:[0,1]
	v_pk_mov_b32 v[120:121], v[2:3], v[2:3] op_sel:[0,1]
	v_pk_mov_b32 v[122:123], v[2:3], v[2:3] op_sel:[0,1]
	v_pk_mov_b32 v[124:125], v[2:3], v[2:3] op_sel:[0,1]
	v_pk_mov_b32 v[126:127], v[2:3], v[2:3] op_sel:[0,1]
	v_pk_mov_b32 v[128:129], v[2:3], v[2:3] op_sel:[0,1]

.LBB0_987:
	s_ashr_i32 s39, s38, 31
	s_lshl_b64 s[40:41], s[38:39], 19
	s_add_u32 s40, s22, s40
	s_addc_u32 s41, s23, s41
	s_and_b64 s[42:43], s[4:5], exec
	s_cselect_b32 s39, s41, s7
	s_cselect_b32 s45, s40, s6
	s_ashr_i32 s37, s36, 31
	s_lshl_b64 s[42:43], s[36:37], 19
	s_add_u32 s42, s3, s42
	s_addc_u32 s43, s62, s43
	s_and_b64 s[48:49], s[4:5], exec
	s_cselect_b32 s37, s43, s47
	s_cselect_b32 s78, s42, s46
	s_add_u32 s6, s6, 0x40080
	s_addc_u32 s7, s7, 0
	s_add_u32 s79, s46, 0x100
	v_mov_b32_e32 v2, 0
	s_addc_u32 s80, s47, 0
	s_mov_b32 s81, -2
	s_waitcnt lgkmcnt(0)
	v_mov_b32_e32 v3, v2
	v_pk_mov_b32 v[4:5], v[2:3], v[2:3] op_sel:[0,1]
	v_pk_mov_b32 v[6:7], v[2:3], v[2:3] op_sel:[0,1]
	v_pk_mov_b32 v[8:9], v[2:3], v[2:3] op_sel:[0,1]
	v_pk_mov_b32 v[10:11], v[2:3], v[2:3] op_sel:[0,1]
	v_pk_mov_b32 v[12:13], v[2:3], v[2:3] op_sel:[0,1]
	v_pk_mov_b32 v[14:15], v[2:3], v[2:3] op_sel:[0,1]
	v_pk_mov_b32 v[16:17], v[2:3], v[2:3] op_sel:[0,1]
	v_pk_mov_b32 v[18:19], v[2:3], v[2:3] op_sel:[0,1]
	v_pk_mov_b32 v[20:21], v[2:3], v[2:3] op_sel:[0,1]
	v_pk_mov_b32 v[22:23], v[2:3], v[2:3] op_sel:[0,1]
	v_pk_mov_b32 v[24:25], v[2:3], v[2:3] op_sel:[0,1]
	v_pk_mov_b32 v[26:27], v[2:3], v[2:3] op_sel:[0,1]
	v_pk_mov_b32 v[28:29], v[2:3], v[2:3] op_sel:[0,1]
	v_pk_mov_b32 v[30:31], v[2:3], v[2:3] op_sel:[0,1]
	v_pk_mov_b32 v[32:33], v[2:3], v[2:3] op_sel:[0,1]
	v_pk_mov_b32 v[34:35], v[2:3], v[2:3] op_sel:[0,1]
	v_pk_mov_b32 v[36:37], v[2:3], v[2:3] op_sel:[0,1]
	v_pk_mov_b32 v[38:39], v[2:3], v[2:3] op_sel:[0,1]
	v_pk_mov_b32 v[40:41], v[2:3], v[2:3] op_sel:[0,1]
	v_pk_mov_b32 v[42:43], v[2:3], v[2:3] op_sel:[0,1]
	v_pk_mov_b32 v[44:45], v[2:3], v[2:3] op_sel:[0,1]
	v_pk_mov_b32 v[46:47], v[2:3], v[2:3] op_sel:[0,1]
	v_pk_mov_b32 v[48:49], v[2:3], v[2:3] op_sel:[0,1]
	v_pk_mov_b32 v[50:51], v[2:3], v[2:3] op_sel:[0,1]
	v_pk_mov_b32 v[52:53], v[2:3], v[2:3] op_sel:[0,1]
	v_pk_mov_b32 v[54:55], v[2:3], v[2:3] op_sel:[0,1]
	v_pk_mov_b32 v[56:57], v[2:3], v[2:3] op_sel:[0,1]
	v_pk_mov_b32 v[58:59], v[2:3], v[2:3] op_sel:[0,1]
	v_pk_mov_b32 v[60:61], v[2:3], v[2:3] op_sel:[0,1]
	v_pk_mov_b32 v[62:63], v[2:3], v[2:3] op_sel:[0,1]
	v_pk_mov_b32 v[64:65], v[2:3], v[2:3] op_sel:[0,1]
	v_pk_mov_b32 v[98:99], v[2:3], v[2:3] op_sel:[0,1]
	v_pk_mov_b32 v[100:101], v[2:3], v[2:3] op_sel:[0,1]
	v_pk_mov_b32 v[102:103], v[2:3], v[2:3] op_sel:[0,1]
	v_pk_mov_b32 v[104:105], v[2:3], v[2:3] op_sel:[0,1]
	v_pk_mov_b32 v[106:107], v[2:3], v[2:3] op_sel:[0,1]
	v_pk_mov_b32 v[108:109], v[2:3], v[2:3] op_sel:[0,1]
	v_pk_mov_b32 v[110:111], v[2:3], v[2:3] op_sel:[0,1]
	v_pk_mov_b32 v[112:113], v[2:3], v[2:3] op_sel:[0,1]
	v_pk_mov_b32 v[114:115], v[2:3], v[2:3] op_sel:[0,1]
	v_pk_mov_b32 v[116:117], v[2:3], v[2:3] op_sel:[0,1]
	v_pk_mov_b32 v[118:119], v[2:3], v[2:3] op_sel:[0,1]
	v_pk_mov_b32 v[120:121], v[2:3], v[2:3] op_sel:[0,1]
	v_pk_mov_b32 v[122:123], v[2:3], v[2:3] op_sel:[0,1]
	v_pk_mov_b32 v[124:125], v[2:3], v[2:3] op_sel:[0,1]
	v_pk_mov_b32 v[126:127], v[2:3], v[2:3] op_sel:[0,1]
	v_pk_mov_b32 v[128:129], v[2:3], v[2:3] op_sel:[0,1]
	v_pk_mov_b32 v[130:131], v[2:3], v[2:3] op_sel:[0,1]
	v_pk_mov_b32 v[132:133], v[2:3], v[2:3] op_sel:[0,1]
	v_pk_mov_b32 v[134:135], v[2:3], v[2:3] op_sel:[0,1]
	v_pk_mov_b32 v[136:137], v[2:3], v[2:3] op_sel:[0,1]
	v_pk_mov_b32 v[138:139], v[2:3], v[2:3] op_sel:[0,1]
	v_pk_mov_b32 v[140:141], v[2:3], v[2:3] op_sel:[0,1]
	v_pk_mov_b32 v[142:143], v[2:3], v[2:3] op_sel:[0,1]
	v_pk_mov_b32 v[144:145], v[2:3], v[2:3] op_sel:[0,1]
	v_pk_mov_b32 v[146:147], v[2:3], v[2:3] op_sel:[0,1]
	v_pk_mov_b32 v[148:149], v[2:3], v[2:3] op_sel:[0,1]
	v_pk_mov_b32 v[150:151], v[2:3], v[2:3] op_sel:[0,1]
	v_pk_mov_b32 v[152:153], v[2:3], v[2:3] op_sel:[0,1]
	v_pk_mov_b32 v[154:155], v[2:3], v[2:3] op_sel:[0,1]
	v_pk_mov_b32 v[156:157], v[2:3], v[2:3] op_sel:[0,1]
	v_pk_mov_b32 v[158:159], v[2:3], v[2:3] op_sel:[0,1]
	v_pk_mov_b32 v[160:161], v[2:3], v[2:3] op_sel:[0,1]

.LBB0_1086:
	s_ashr_i32 s17, s16, 31
	s_lshl_b64 s[18:19], s[16:17], 19
	s_add_u32 s18, s38, s18
	s_addc_u32 s19, s39, s19
	s_and_b64 s[22:23], s[0:1], exec
	s_cselect_b32 s17, s19, s27
	s_cselect_b32 s65, s18, s26
	s_ashr_i32 s15, s14, 31
	s_lshl_b64 s[22:23], s[14:15], 19
	s_add_u32 s22, s40, s22
	s_addc_u32 s23, s41, s23
	s_and_b64 s[30:31], s[0:1], exec
	s_cselect_b32 s15, s23, s29
	s_cselect_b32 s66, s22, s28
	s_add_u32 s26, s26, 0x40080
	s_addc_u32 s27, s27, 0
	s_add_u32 s67, s28, 0x100
	v_mov_b32_e32 v2, 0
	s_addc_u32 s68, s29, 0
	s_mov_b32 s69, -2
	v_mov_b32_e32 v3, v2
	v_pk_mov_b32 v[4:5], v[2:3], v[2:3] op_sel:[0,1]
	v_pk_mov_b32 v[6:7], v[2:3], v[2:3] op_sel:[0,1]
	v_pk_mov_b32 v[8:9], v[2:3], v[2:3] op_sel:[0,1]
	v_pk_mov_b32 v[10:11], v[2:3], v[2:3] op_sel:[0,1]
	v_pk_mov_b32 v[12:13], v[2:3], v[2:3] op_sel:[0,1]
	v_pk_mov_b32 v[14:15], v[2:3], v[2:3] op_sel:[0,1]
	v_pk_mov_b32 v[16:17], v[2:3], v[2:3] op_sel:[0,1]
	v_pk_mov_b32 v[18:19], v[2:3], v[2:3] op_sel:[0,1]
	v_pk_mov_b32 v[20:21], v[2:3], v[2:3] op_sel:[0,1]
	v_pk_mov_b32 v[22:23], v[2:3], v[2:3] op_sel:[0,1]
	v_pk_mov_b32 v[24:25], v[2:3], v[2:3] op_sel:[0,1]
	v_pk_mov_b32 v[26:27], v[2:3], v[2:3] op_sel:[0,1]
	v_pk_mov_b32 v[28:29], v[2:3], v[2:3] op_sel:[0,1]
	v_pk_mov_b32 v[30:31], v[2:3], v[2:3] op_sel:[0,1]
	v_pk_mov_b32 v[32:33], v[2:3], v[2:3] op_sel:[0,1]
	v_pk_mov_b32 v[34:35], v[2:3], v[2:3] op_sel:[0,1]
	v_pk_mov_b32 v[36:37], v[2:3], v[2:3] op_sel:[0,1]
	v_pk_mov_b32 v[38:39], v[2:3], v[2:3] op_sel:[0,1]
	v_pk_mov_b32 v[40:41], v[2:3], v[2:3] op_sel:[0,1]
	v_pk_mov_b32 v[42:43], v[2:3], v[2:3] op_sel:[0,1]
	v_pk_mov_b32 v[44:45], v[2:3], v[2:3] op_sel:[0,1]
	v_pk_mov_b32 v[46:47], v[2:3], v[2:3] op_sel:[0,1]
	v_pk_mov_b32 v[48:49], v[2:3], v[2:3] op_sel:[0,1]
	v_pk_mov_b32 v[50:51], v[2:3], v[2:3] op_sel:[0,1]
	v_pk_mov_b32 v[52:53], v[2:3], v[2:3] op_sel:[0,1]
	v_pk_mov_b32 v[54:55], v[2:3], v[2:3] op_sel:[0,1]
	v_pk_mov_b32 v[56:57], v[2:3], v[2:3] op_sel:[0,1]
	v_pk_mov_b32 v[58:59], v[2:3], v[2:3] op_sel:[0,1]
	v_pk_mov_b32 v[60:61], v[2:3], v[2:3] op_sel:[0,1]
	v_pk_mov_b32 v[62:63], v[2:3], v[2:3] op_sel:[0,1]
	v_pk_mov_b32 v[64:65], v[2:3], v[2:3] op_sel:[0,1]
	v_pk_mov_b32 v[66:67], v[2:3], v[2:3] op_sel:[0,1]
	v_pk_mov_b32 v[68:69], v[2:3], v[2:3] op_sel:[0,1]
	v_pk_mov_b32 v[70:71], v[2:3], v[2:3] op_sel:[0,1]
	v_pk_mov_b32 v[72:73], v[2:3], v[2:3] op_sel:[0,1]
	v_pk_mov_b32 v[74:75], v[2:3], v[2:3] op_sel:[0,1]
	v_pk_mov_b32 v[76:77], v[2:3], v[2:3] op_sel:[0,1]
	v_pk_mov_b32 v[78:79], v[2:3], v[2:3] op_sel:[0,1]
	v_pk_mov_b32 v[80:81], v[2:3], v[2:3] op_sel:[0,1]
	v_pk_mov_b32 v[82:83], v[2:3], v[2:3] op_sel:[0,1]
	v_pk_mov_b32 v[84:85], v[2:3], v[2:3] op_sel:[0,1]
	v_pk_mov_b32 v[86:87], v[2:3], v[2:3] op_sel:[0,1]
	v_pk_mov_b32 v[88:89], v[2:3], v[2:3] op_sel:[0,1]
	v_pk_mov_b32 v[90:91], v[2:3], v[2:3] op_sel:[0,1]
	v_pk_mov_b32 v[92:93], v[2:3], v[2:3] op_sel:[0,1]
	v_pk_mov_b32 v[94:95], v[2:3], v[2:3] op_sel:[0,1]
	v_pk_mov_b32 v[96:97], v[2:3], v[2:3] op_sel:[0,1]
	v_pk_mov_b32 v[98:99], v[2:3], v[2:3] op_sel:[0,1]
	v_pk_mov_b32 v[100:101], v[2:3], v[2:3] op_sel:[0,1]
	v_pk_mov_b32 v[102:103], v[2:3], v[2:3] op_sel:[0,1]
	v_pk_mov_b32 v[104:105], v[2:3], v[2:3] op_sel:[0,1]
	v_pk_mov_b32 v[106:107], v[2:3], v[2:3] op_sel:[0,1]
	v_pk_mov_b32 v[108:109], v[2:3], v[2:3] op_sel:[0,1]
	v_pk_mov_b32 v[110:111], v[2:3], v[2:3] op_sel:[0,1]
	v_pk_mov_b32 v[112:113], v[2:3], v[2:3] op_sel:[0,1]
	v_pk_mov_b32 v[114:115], v[2:3], v[2:3] op_sel:[0,1]
	v_pk_mov_b32 v[116:117], v[2:3], v[2:3] op_sel:[0,1]
	v_pk_mov_b32 v[118:119], v[2:3], v[2:3] op_sel:[0,1]
	v_pk_mov_b32 v[120:121], v[2:3], v[2:3] op_sel:[0,1]
	v_pk_mov_b32 v[122:123], v[2:3], v[2:3] op_sel:[0,1]
	v_pk_mov_b32 v[124:125], v[2:3], v[2:3] op_sel:[0,1]
	v_pk_mov_b32 v[126:127], v[2:3], v[2:3] op_sel:[0,1]
	v_pk_mov_b32 v[128:129], v[2:3], v[2:3] op_sel:[0,1]

.LBB0_1167:
	s_add_u32 s26, s26, 0xb0080
	s_addc_u32 s27, s27, 0
	s_add_u32 s23, s28, 0x100
	v_mov_b32_e32 v0, 0
	s_addc_u32 s25, s29, 0
	s_mov_b32 s59, -2
	v_mov_b32_e32 v1, v0
	v_pk_mov_b32 v[2:3], v[0:1], v[0:1] op_sel:[0,1]
	v_pk_mov_b32 v[4:5], v[0:1], v[0:1] op_sel:[0,1]
	v_pk_mov_b32 v[6:7], v[0:1], v[0:1] op_sel:[0,1]
	v_pk_mov_b32 v[8:9], v[0:1], v[0:1] op_sel:[0,1]
	v_pk_mov_b32 v[10:11], v[0:1], v[0:1] op_sel:[0,1]
	v_pk_mov_b32 v[12:13], v[0:1], v[0:1] op_sel:[0,1]
	v_pk_mov_b32 v[14:15], v[0:1], v[0:1] op_sel:[0,1]
	v_pk_mov_b32 v[16:17], v[0:1], v[0:1] op_sel:[0,1]
	v_pk_mov_b32 v[18:19], v[0:1], v[0:1] op_sel:[0,1]
	v_pk_mov_b32 v[20:21], v[0:1], v[0:1] op_sel:[0,1]
	v_pk_mov_b32 v[22:23], v[0:1], v[0:1] op_sel:[0,1]
	v_pk_mov_b32 v[24:25], v[0:1], v[0:1] op_sel:[0,1]
	v_pk_mov_b32 v[26:27], v[0:1], v[0:1] op_sel:[0,1]
	v_pk_mov_b32 v[28:29], v[0:1], v[0:1] op_sel:[0,1]
	v_pk_mov_b32 v[30:31], v[0:1], v[0:1] op_sel:[0,1]
	v_pk_mov_b32 v[32:33], v[0:1], v[0:1] op_sel:[0,1]
	v_pk_mov_b32 v[34:35], v[0:1], v[0:1] op_sel:[0,1]
	v_pk_mov_b32 v[36:37], v[0:1], v[0:1] op_sel:[0,1]
	v_pk_mov_b32 v[38:39], v[0:1], v[0:1] op_sel:[0,1]
	v_pk_mov_b32 v[40:41], v[0:1], v[0:1] op_sel:[0,1]
	v_pk_mov_b32 v[42:43], v[0:1], v[0:1] op_sel:[0,1]
	v_pk_mov_b32 v[44:45], v[0:1], v[0:1] op_sel:[0,1]
	v_pk_mov_b32 v[46:47], v[0:1], v[0:1] op_sel:[0,1]
	v_pk_mov_b32 v[48:49], v[0:1], v[0:1] op_sel:[0,1]
	v_pk_mov_b32 v[50:51], v[0:1], v[0:1] op_sel:[0,1]
	v_pk_mov_b32 v[52:53], v[0:1], v[0:1] op_sel:[0,1]
	v_pk_mov_b32 v[54:55], v[0:1], v[0:1] op_sel:[0,1]
	v_pk_mov_b32 v[56:57], v[0:1], v[0:1] op_sel:[0,1]
	v_pk_mov_b32 v[58:59], v[0:1], v[0:1] op_sel:[0,1]
	v_pk_mov_b32 v[60:61], v[0:1], v[0:1] op_sel:[0,1]
	v_pk_mov_b32 v[62:63], v[0:1], v[0:1] op_sel:[0,1]
	v_pk_mov_b32 v[64:65], v[0:1], v[0:1] op_sel:[0,1]
	v_pk_mov_b32 v[66:67], v[0:1], v[0:1] op_sel:[0,1]
	v_pk_mov_b32 v[68:69], v[0:1], v[0:1] op_sel:[0,1]
	v_pk_mov_b32 v[70:71], v[0:1], v[0:1] op_sel:[0,1]
	v_pk_mov_b32 v[72:73], v[0:1], v[0:1] op_sel:[0,1]
	v_pk_mov_b32 v[74:75], v[0:1], v[0:1] op_sel:[0,1]
	v_pk_mov_b32 v[76:77], v[0:1], v[0:1] op_sel:[0,1]
	v_pk_mov_b32 v[78:79], v[0:1], v[0:1] op_sel:[0,1]
	v_pk_mov_b32 v[80:81], v[0:1], v[0:1] op_sel:[0,1]
	v_pk_mov_b32 v[82:83], v[0:1], v[0:1] op_sel:[0,1]
	v_pk_mov_b32 v[84:85], v[0:1], v[0:1] op_sel:[0,1]
	v_pk_mov_b32 v[86:87], v[0:1], v[0:1] op_sel:[0,1]
	v_pk_mov_b32 v[88:89], v[0:1], v[0:1] op_sel:[0,1]
	v_pk_mov_b32 v[90:91], v[0:1], v[0:1] op_sel:[0,1]
	v_pk_mov_b32 v[92:93], v[0:1], v[0:1] op_sel:[0,1]
	v_pk_mov_b32 v[94:95], v[0:1], v[0:1] op_sel:[0,1]
	v_pk_mov_b32 v[96:97], v[0:1], v[0:1] op_sel:[0,1]
	v_pk_mov_b32 v[98:99], v[0:1], v[0:1] op_sel:[0,1]
	v_pk_mov_b32 v[100:101], v[0:1], v[0:1] op_sel:[0,1]
	v_pk_mov_b32 v[102:103], v[0:1], v[0:1] op_sel:[0,1]
	v_pk_mov_b32 v[112:113], v[0:1], v[0:1] op_sel:[0,1]
	v_pk_mov_b32 v[114:115], v[0:1], v[0:1] op_sel:[0,1]
	v_pk_mov_b32 v[120:121], v[0:1], v[0:1] op_sel:[0,1]
	v_pk_mov_b32 v[122:123], v[0:1], v[0:1] op_sel:[0,1]
	v_pk_mov_b32 v[128:129], v[0:1], v[0:1] op_sel:[0,1]
	v_pk_mov_b32 v[130:131], v[0:1], v[0:1] op_sel:[0,1]
	v_pk_mov_b32 v[132:133], v[0:1], v[0:1] op_sel:[0,1]
	v_pk_mov_b32 v[134:135], v[0:1], v[0:1] op_sel:[0,1]
	v_pk_mov_b32 v[136:137], v[0:1], v[0:1] op_sel:[0,1]
	v_pk_mov_b32 v[138:139], v[0:1], v[0:1] op_sel:[0,1]
	v_pk_mov_b32 v[140:141], v[0:1], v[0:1] op_sel:[0,1]
	v_pk_mov_b32 v[142:143], v[0:1], v[0:1] op_sel:[0,1]
